# P0 balance: the 16 extra x rows and the SSM table conversion run on the workgroups that got one weight-transpose item less (248..255) instead of workgroups 0..7
# speedup vs baseline: 1.0144x; 1.0052x over previous
; __device__ __forceinline__ void p0_prologue(const Args& a, LAS unsigned char* lds, int wave, int lane) {
;     ...
;     bf16* XB = (bf16*)(ws + WS_XB); float* rstdx = (float*)(ws + WS_RSTDX);
;     for (int m0 = gw; m0 < NTOK + 16; m0 += 2 * NGW) {
;         const int m1 = m0 + NGW; const bool has1 = m1 < NTOK + 16; const int m1c = has1 ? m1 : m0;
;         const float* src0 = m0 < NTOK ? a.in[0] + (size_t)m0 * DM : a.in[1] + (size_t)(m0 - NTOK) * DM;
;         const float* src1 = m1c < NTOK ? a.in[0] + (size_t)m1c * DM : a.in[1] + (size_t)(m1c - NTOK) * DM;
;         f32x4 v0[4], v1[4]; float s0 = 0.f, s1 = 0.f;
; #pragma unroll
;         for (int j = 0; j < 4; ++j) { v0[j] = __builtin_nontemporal_load((const f32x4*)src0 + lane + 64 * j); v1[j] = __builtin_nontemporal_load((const f32x4*)src1 + lane + 64 * j); }
.LBB0_88:
	s_cmp_gt_i32 s38, 0x800f
	v_cmp_eq_u32_e64 s[0:1], 0, v128
	v_mbcnt_lo_u32_b32 v235, -1, 0
	s_cbranch_scc1 .LBB0_100
	v_mov_b32_e32 v33, 0
	v_lshlrev_b32_e32 v32, 3, v128
	v_lshl_add_u64 v[0:1], s[58:59], 0, v[32:33]
	s_mov_b64 s[4:5], 0x2c00000
	v_lshl_add_u64 v[34:35], v[0:1], 0, s[4:5]
	s_mov_b32 s4, s97
	s_ashr_i32 s97, s96, 31
	s_mov_b32 s7, 0
	v_lshlrev_b32_e32 v32, 4, v128
	v_mbcnt_hi_u32_b32 v36, -1, v235
	v_mov_b32_e32 v37, 0x358637bd
	s_lshl_b64 s[8:9], s[96:97], 2
	s_mov_b32 s97, s4
	s_add_i32 s10, s38, 64
	s_and_b32 s10, s10, 0x7ff
	s_branch .LBB0_91

; __device__ __forceinline__ void p0_prologue(const Args& a, LAS unsigned char* lds, int wave, int lane) {
;     ...
;     if (gt < NGRP * NST) {
;         const int g = gt >> 6, p = gt & 63;
;         const float dt = expf(a.in[9][g]), lr = a.in[7][gt], li = a.in[8][gt];
;         const float mag = expf(lr * dt); float sn, cs; sincos_small(li * dt, sn, cs);
;         const float ar = mag * cs, ai = mag * sn, den = lr * lr + li * li, nr = ar - 1.0f, ni = ai;
;         const float fr = (nr * lr + ni * li) / den, fi = (ni * lr - nr * li) / den;
;         ((f32x2*)(ws + WS_ATAB))[gt] = (f32x2){ar, ai};
;         float pr = ar, pi = ai;
; #pragma unroll
;         for (int i = 0; i < 8; ++i) { const float tr = pr * pr - pi * pi, ti = 2.0f * pr * pi; pr = tr; pi = ti; }
;         ((f32x2*)(ws + WS_ATAB2))[gt] = (f32x2){pr, pi};
;         bf16* BB = (bf16*)(ws + WS_BB); bf16* CM = (bf16*)(ws + WS_CM);
;         const int rre = g * 128 + (p >> 5) * 64 + (p & 31), rim = rre + 32;
;         const float* bre = a.in[10] + (size_t)gt * 16; const float* bim = a.in[11] + (size_t)gt * 16;
.LBB0_103:
	s_or_b64 exec, exec, s[0:1]
	v_add_u32_e32 v2, 0xfffe1000, v2
	s_movk_i32 s0, 0x1000
	v_cmp_gt_u32_e32 vcc, s0, v2
	v_and_b32_e32 v130, 31, v224
	s_and_saveexec_b64 s[4:5], vcc
	s_cbranch_execz .LBB0_105
	v_ashrrev_i32_e32 v0, 6, v2
	v_mov_b32_e32 v4, s62
	v_mov_b32_e32 v5, s63
	v_ashrrev_i32_e32 v1, 31, v0
	v_lshl_add_u64 v[4:5], v[0:1], 2, v[4:5]
	global_load_dword v9, v[4:5], off
	v_lshlrev_b64 v[4:5], 2, v[2:3]
	v_lshl_add_u64 v[6:7], s[90:91], 0, v[4:5]
	v_lshl_add_u64 v[4:5], s[60:61], 0, v[4:5]
	global_load_dword v22, v[6:7], off
	global_load_dword v23, v[4:5], off
	s_mov_b32 s10, 0x3fb8aa3b
	v_lshl_add_u64 v[6:7], v[2:3], 3, s[58:59]
	s_mov_b32 s11, 0x80000
	v_add_co_u32_e32 v10, vcc, s11, v6
	s_mov_b32 s12, 0x88000
	s_nop 0
	v_addc_co_u32_e32 v11, vcc, 0, v7, vcc
	v_add_co_u32_e32 v6, vcc, s12, v6
	s_mov_b32 s9, 0xc2ce8ed0
	s_nop 0
	v_addc_co_u32_e32 v7, vcc, 0, v7, vcc
	s_mov_b32 s8, 0x42b17218
	v_mov_b32_e32 v12, 0x7f800000
	s_mov_b32 s0, 0x37ccf5ce
	s_mov_b32 s1, 0x394ca1f9
	v_mov_b32_e32 v4, 0xbab6061a
	v_mov_b32_e32 v5, 0x3c08839e
	s_mov_b32 s6, 0x3d2aaaa5
	s_mov_b32 s7, 0xbe2aaaa3
	v_mov_b32_e32 v8, 2.0
	v_mov_b32_e32 v13, v8
	v_lshlrev_b64 v[2:3], 6, v[2:3]
	s_waitcnt vmcnt(2)
	v_mul_f32_e32 v14, 0x3fb8aa3b, v9
	v_fma_f32 v15, v9, s10, -v14
	v_rndne_f32_e32 v16, v14
	v_fmac_f32_e32 v15, 0x32a5705f, v9
	v_sub_f32_e32 v14, v14, v16
	v_add_f32_e32 v14, v14, v15
	v_cvt_i32_f32_e32 v16, v16
	v_exp_f32_e32 v14, v14
	v_cmp_ngt_f32_e32 vcc, s9, v9
	v_ldexp_f32 v14, v14, v16
	s_nop 0
	v_cndmask_b32_e32 v14, 0, v14, vcc
	v_cmp_nlt_f32_e32 vcc, s8, v9
	s_nop 1
	v_cndmask_b32_e32 v9, v12, v14, vcc
	s_waitcnt vmcnt(1)
	v_mul_f32_e32 v24, v9, v22
	s_waitcnt vmcnt(0)
	v_mul_f32_e32 v9, v9, v23
	v_mul_f32_e32 v14, 0x3fb8aa3b, v24
	v_mul_f32_e32 v15, 0x3f22f983, v9
	v_fma_f32 v16, v24, s10, -v14
	v_rndne_f32_e32 v17, v14
	v_rndne_f32_e32 v15, v15
	v_fmac_f32_e32 v16, 0x32a5705f, v24
	v_sub_f32_e32 v14, v14, v17
	v_fmamk_f32 v9, v15, 0xbfc90000, v9
	v_add_f32_e32 v14, v14, v16
	v_cvt_i32_f32_e32 v25, v17
	v_fmamk_f32 v9, v15, 0xb9fda000, v9
	v_exp_f32_e32 v27, v14
	v_cvt_i32_f32_e32 v26, v15
	v_fmamk_f32 v15, v15, 0xb3a22169, v9
	v_mul_f32_e32 v14, v15, v15
	v_pk_fma_f32 v[20:21], v[14:15], s[0:1], v[4:5]
	v_pk_fma_f32 v[4:5], v[14:15], s[0:1], v[4:5] op_sel_hi:[0,1,1] neg_lo:[1,0,0] neg_hi:[1,0,0]
	v_mov_b32_e32 v21, v5
	v_ldexp_f32 v25, v27, v25
	v_cmp_ngt_f32_e32 vcc, s9, v24
	v_mov_b32_e32 v17, v15
	v_fma_f32 v16, v14, -0.5, 1.0
	v_and_b32_e32 v9, 1, v26
	v_pk_mul_f32 v[18:19], v[14:15], v[14:15] op_sel_hi:[1,0]
	v_pk_fma_f32 v[4:5], v[14:15], v[20:21], s[6:7] op_sel_hi:[0,1,1]
	v_cndmask_b32_e32 v14, 0, v25, vcc
	v_cmp_nlt_f32_e32 vcc, s8, v24
	v_add_u32_e32 v28, 1, v26
	v_and_b32_e32 v26, 2, v26
	v_pk_fma_f32 v[4:5], v[18:19], v[4:5], v[16:17]
	v_cndmask_b32_e32 v12, v12, v14, vcc
	v_cmp_eq_u32_e32 vcc, 0, v9
	v_and_b32_e32 v28, 2, v28
	s_add_u32 s6, s58, 0x100000
	v_cndmask_b32_e32 v9, v5, v4, vcc
	v_cndmask_b32_e32 v4, v4, v5, vcc
	v_cmp_eq_u32_e32 vcc, 0, v26
	s_addc_u32 s7, s59, 0
	s_nop 0
	v_cndmask_b32_e64 v5, -v4, v4, vcc
	v_cmp_eq_u32_e32 vcc, 0, v28
	s_nop 1
	v_cndmask_b32_e64 v4, -v9, v9, vcc
	v_pk_mul_f32 v[4:5], v[12:13], v[4:5] op_sel_hi:[0,1]
	global_store_dwordx2 v[10:11], v[4:5], off
	v_mul_f32_e32 v10, v5, v5
	v_add_f32_e32 v9, v4, v4
	v_pk_fma_f32 v[10:11], v[4:5], v[4:5], v[10:11] op_sel_hi:[1,1,0] neg_lo:[0,0,1] neg_hi:[0,0,1]
	v_mul_f32_e32 v14, v5, v9
	v_mov_b32_e32 v9, v10
	v_mul_f32_e32 v15, v14, v14
	v_pk_mul_f32 v[16:17], v[10:11], v[8:9] op_sel_hi:[0,1]
	v_pk_fma_f32 v[10:11], v[10:11], v[8:9], v[14:15] op_sel_hi:[0,1,1] neg_lo:[0,0,1] neg_hi:[0,0,1]
	v_pk_mul_f32 v[14:15], v[16:17], v[14:15]
	v_mul_f32_e32 v10, v11, v11
	v_mov_b32_e32 v15, v11
	v_add_f32_e32 v9, v11, v11
	v_pk_fma_f32 v[10:11], v[14:15], v[14:15], v[10:11] op_sel_hi:[1,1,0] neg_lo:[1,0,0] neg_hi:[1,0,0]
	v_add_f32_e32 v4, -1.0, v4
	v_mul_f32_e32 v11, v14, v9
	v_mul_f32_e32 v12, v10, v10
	v_pk_fma_f32 v[14:15], v[10:11], v[10:11], v[12:13] op_sel_hi:[1,1,0] neg_lo:[1,0,0] neg_hi:[1,0,0]
	v_add_f32_e32 v16, v10, v10
	v_mov_b32_e32 v10, v11
	v_mov_b32_e32 v11, v15
	v_mov_b32_e32 v17, v15
	v_pk_mul_f32 v[10:11], v[10:11], v[16:17]
	s_nop 0
	v_pk_mov_b32 v[14:15], v[14:15], v[10:11] op_sel:[1,0]
	v_mov_b32_e32 v9, v10
	v_pk_mul_f32 v[16:17], v[14:15], v[8:9]
	v_pk_fma_f32 v[8:9], v[14:15], v[8:9], v[10:11] neg_lo:[1,0,0] neg_hi:[1,0,0]
	v_pk_mul_f32 v[10:11], v[10:11], v[16:17]
	v_mul_f32_e32 v8, v9, v9
	v_mov_b32_e32 v11, v9
	v_add_f32_e32 v12, v9, v9
	v_pk_fma_f32 v[8:9], v[10:11], v[10:11], v[8:9] op_sel_hi:[1,1,0] neg_lo:[1,0,0] neg_hi:[1,0,0]
	v_mul_f32_e32 v16, v22, v4
	v_mul_f32_e32 v9, v10, v12
	v_add_f32_e32 v11, v8, v8
	v_mul_f32_e32 v10, v9, v9
	v_pk_fma_f32 v[14:15], v[8:9], v[8:9], v[10:11] op_sel_hi:[1,1,0] neg_lo:[0,0,1] neg_hi:[0,0,1]
	v_mul_f32_e32 v4, v23, v4
	v_mov_b32_e32 v8, v14
	v_mov_b32_e32 v10, v14
	v_pk_mul_f32 v[8:9], v[8:9], v[10:11]
	v_fmac_f32_e32 v16, v23, v5
	v_pk_mov_b32 v[10:11], v[8:9], v[14:15] op_sel:[1,0]
	v_mov_b32_e32 v12, v9
	v_pk_add_f32 v[14:15], v[10:11], v[10:11]
	v_pk_fma_f32 v[10:11], v[10:11], v[12:13], v[8:9] neg_lo:[1,0,0] neg_hi:[1,0,0]
	v_pk_mul_f32 v[8:9], v[8:9], v[14:15]
	v_lshlrev_b32_e32 v12, 1, v224
	v_mov_b32_e32 v11, v9
	global_store_dwordx2 v[6:7], v[10:11], off
	v_lshl_add_u64 v[6:7], s[66:67], 0, v[2:3]
	v_lshl_add_u64 v[2:3], s[64:65], 0, v[2:3]
	global_load_dwordx4 v[32:35], v[6:7], off
	global_load_dwordx4 v[36:39], v[6:7], off offset:16
	global_load_dwordx4 v[40:43], v[6:7], off offset:32
	global_load_dwordx4 v[44:47], v[6:7], off offset:48
	global_load_dwordx4 v[48:51], v[2:3], off
; __device__ __forceinline__ unsigned cvt_pk(float lo, float hi) { unsigned r; asm volatile("v_cvt_pk_bf16_f32 %0, %1, %2" : "=v"(r) : "v"(lo), "v"(hi)); return r; }
; __device__ __forceinline__ void p0_prologue(const Args& a, LAS unsigned char* lds, int wave, int lane) {
;     ...
;         const float fr = (nr * lr + ni * li) / den, fi = (ni * lr - nr * li) / den;
;         ((f32x2*)(ws + WS_ATAB))[gt] = (f32x2){ar, ai};
;         float pr = ar, pi = ai;
; #pragma unroll
;         for (int i = 0; i < 8; ++i) { const float tr = pr * pr - pi * pi, ti = 2.0f * pr * pi; pr = tr; pi = ti; }
;         ((f32x2*)(ws + WS_ATAB2))[gt] = (f32x2){pr, pi};
;         bf16* BB = (bf16*)(ws + WS_BB); bf16* CM = (bf16*)(ws + WS_CM);
;         const int rre = g * 128 + (p >> 5) * 64 + (p & 31), rim = rre + 32;
;         const float* bre = a.in[10] + (size_t)gt * 16; const float* bim = a.in[11] + (size_t)gt * 16;
; #pragma unroll
;         for (int c = 0; c < 16; c += 2) {
;             const float br0 = bre[c], bi0 = bim[c], br1 = bre[c + 1], bi1 = bim[c + 1];
;             *(unsigned*)(BB + (size_t)rre * 16 + c) = cvt_pk(fr * br0 - fi * bi0, fr * br1 - fi * bi1);
;             *(unsigned*)(BB + (size_t)rim * 16 + c) = cvt_pk(fr * bi0 + fi * br0, fr * bi1 + fi * br1);
;         }
; #pragma unroll
;         for (int c = 0; c < 16; ++c) {
;             const float cr = a.in[12][((size_t)g * 16 + c) * 64 + p], ci = a.in[13][((size_t)g * 16 + c) * 64 + p];
;             *(unsigned*)(CM + ((size_t)g * 16 + c) * 128 + 2 * p) = cvt_pk(cr, -ci);
;         }
	global_load_dwordx4 v[52:55], v[2:3], off offset:16
	global_load_dwordx4 v[56:59], v[2:3], off offset:32
	global_load_dwordx4 v[60:63], v[2:3], off offset:48
	v_lshlrev_b32_e32 v13, 7, v0
	v_and_b32_e32 v12, 64, v12
	v_or3_b32 v12, v13, v12, v130
	v_ashrrev_i32_e32 v13, 31, v12
	v_lshlrev_b64 v[14:15], 5, v[12:13]
	v_lshlrev_b64 v[0:1], 12, v[0:1]
	v_lshlrev_b32_e32 v100, 2, v128
	v_or_b32_e32 v100, v0, v100
	v_mov_b32_e32 v101, v1
	v_lshl_add_u64 v[96:97], s[68:69], 0, v[100:101]
	v_lshl_add_u64 v[98:99], s[70:71], 0, v[100:101]
	global_load_dword v64, v[96:97], off
	global_load_dword v65, v[96:97], off offset:256
	global_load_dword v66, v[96:97], off offset:512
	global_load_dword v67, v[96:97], off offset:768
	global_load_dword v68, v[96:97], off offset:1024
	global_load_dword v69, v[96:97], off offset:1280
	global_load_dword v70, v[96:97], off offset:1536
	global_load_dword v71, v[96:97], off offset:1792
	global_load_dword v72, v[96:97], off offset:2048
	global_load_dword v73, v[96:97], off offset:2304
	global_load_dword v74, v[96:97], off offset:2560
	global_load_dword v75, v[96:97], off offset:2816
	global_load_dword v76, v[96:97], off offset:3072
	global_load_dword v77, v[96:97], off offset:3328
	global_load_dword v78, v[96:97], off offset:3584
	global_load_dword v79, v[96:97], off offset:3840
	global_load_dword v80, v[98:99], off
	global_load_dword v81, v[98:99], off offset:256
	global_load_dword v82, v[98:99], off offset:512
	global_load_dword v83, v[98:99], off offset:768
	global_load_dword v84, v[98:99], off offset:1024
	global_load_dword v85, v[98:99], off offset:1280
	global_load_dword v86, v[98:99], off offset:1536
	global_load_dword v87, v[98:99], off offset:1792
	global_load_dword v88, v[98:99], off offset:2048
	global_load_dword v89, v[98:99], off offset:2304
	global_load_dword v90, v[98:99], off offset:2560
	global_load_dword v91, v[98:99], off offset:2816
	global_load_dword v92, v[98:99], off offset:3072
	global_load_dword v93, v[98:99], off offset:3328
	global_load_dword v94, v[98:99], off offset:3584
	global_load_dword v95, v[98:99], off offset:3840
	v_mul_f32_e32 v13, v23, v23
	v_fmac_f32_e32 v13, v22, v22
	v_fma_f32 v4, v22, v5, -v4
	v_div_scale_f32 v5, s[0:1], v13, v13, v16
	v_div_scale_f32 v18, s[0:1], v13, v13, v4
	v_rcp_f32_e32 v19, v5
	v_rcp_f32_e32 v20, v18
	v_div_scale_f32 v17, vcc, v16, v13, v16
	v_fma_f32 v22, -v5, v19, 1.0
	v_fma_f32 v23, -v18, v20, 1.0
	v_fmac_f32_e32 v19, v22, v19
	v_div_scale_f32 v21, s[0:1], v4, v13, v4
	v_fmac_f32_e32 v20, v23, v20
	v_mul_f32_e32 v22, v17, v19
	v_mul_f32_e32 v23, v21, v20
	v_fma_f32 v24, -v5, v22, v17
	v_fma_f32 v25, -v18, v23, v21
	v_fmac_f32_e32 v22, v24, v19
	v_fmac_f32_e32 v23, v25, v20
	v_fma_f32 v5, -v5, v22, v17
	v_fma_f32 v17, -v18, v23, v21
	v_div_fmas_f32 v5, v5, v19, v22
	s_mov_b64 vcc, s[0:1]
	v_div_fixup_f32 v16, v5, v13, v16
	v_div_fmas_f32 v5, v17, v20, v23
	v_div_fixup_f32 v17, v5, v13, v4
	v_lshl_add_u64 v[14:15], s[6:7], 0, v[14:15]
	s_add_u32 s8, s58, 0x140000
	s_addc_u32 s9, s59, 0
	v_lshl_add_u64 v[100:101], s[8:9], 0, v[100:101]
	s_waitcnt vmcnt(32)
; __device__ __forceinline__ unsigned cvt_pk(float lo, float hi) { unsigned r; asm volatile("v_cvt_pk_bf16_f32 %0, %1, %2" : "=v"(r) : "v"(lo), "v"(hi)); return r; }
; __device__ __forceinline__ void p0_prologue(const Args& a, LAS unsigned char* lds, int wave, int lane) {
;     ...
;         for (int c = 0; c < 16; c += 2) {
;             const float br0 = bre[c], bi0 = bim[c], br1 = bre[c + 1], bi1 = bim[c + 1];
;             *(unsigned*)(BB + (size_t)rre * 16 + c) = cvt_pk(fr * br0 - fi * bi0, fr * br1 - fi * bi1);
;             *(unsigned*)(BB + (size_t)rim * 16 + c) = cvt_pk(fr * bi0 + fi * br0, fr * bi1 + fi * br1);
;         }
; #pragma unroll
;         for (int c = 0; c < 16; ++c) {
;             const float cr = a.in[12][((size_t)g * 16 + c) * 64 + p], ci = a.in[13][((size_t)g * 16 + c) * 64 + p];
;             *(unsigned*)(CM + ((size_t)g * 16 + c) * 128 + 2 * p) = cvt_pk(cr, -ci);
;         }
	v_mul_f32_e32 v4, v32, v17
	v_mul_f32_e32 v5, v33, v17
	v_mul_f32_e32 v8, v32, v16
	v_mul_f32_e32 v9, v33, v16
	v_fma_f32 v4, v48, v16, -v4
	v_fma_f32 v5, v49, v16, -v5
	v_fmac_f32_e32 v8, v48, v17
	v_fmac_f32_e32 v9, v49, v17
	v_cvt_pk_bf16_f32 v104, v4, v5
	v_cvt_pk_bf16_f32 v116, v8, v9
	v_mul_f32_e32 v4, v34, v17
	v_mul_f32_e32 v5, v35, v17
	v_mul_f32_e32 v8, v34, v16
	v_mul_f32_e32 v9, v35, v16
	v_fma_f32 v4, v50, v16, -v4
	v_fma_f32 v5, v51, v16, -v5
	v_fmac_f32_e32 v8, v50, v17
	v_fmac_f32_e32 v9, v51, v17
	v_cvt_pk_bf16_f32 v105, v4, v5
	v_cvt_pk_bf16_f32 v117, v8, v9
	v_mul_f32_e32 v4, v36, v17
	v_mul_f32_e32 v5, v37, v17
	v_mul_f32_e32 v8, v36, v16
	v_mul_f32_e32 v9, v37, v16
	v_fma_f32 v4, v52, v16, -v4
	v_fma_f32 v5, v53, v16, -v5
	v_fmac_f32_e32 v8, v52, v17
	v_fmac_f32_e32 v9, v53, v17
	v_cvt_pk_bf16_f32 v106, v4, v5
	v_cvt_pk_bf16_f32 v118, v8, v9
	v_mul_f32_e32 v4, v38, v17
	v_mul_f32_e32 v5, v39, v17
	v_mul_f32_e32 v8, v38, v16
	v_mul_f32_e32 v9, v39, v16
	v_fma_f32 v4, v54, v16, -v4
	v_fma_f32 v5, v55, v16, -v5
	v_fmac_f32_e32 v8, v54, v17
	v_fmac_f32_e32 v9, v55, v17
	v_cvt_pk_bf16_f32 v107, v4, v5
	v_cvt_pk_bf16_f32 v119, v8, v9
	v_mul_f32_e32 v4, v40, v17
	v_mul_f32_e32 v5, v41, v17
	v_mul_f32_e32 v8, v40, v16
	v_mul_f32_e32 v9, v41, v16
	v_fma_f32 v4, v56, v16, -v4
	v_fma_f32 v5, v57, v16, -v5
	v_fmac_f32_e32 v8, v56, v17
	v_fmac_f32_e32 v9, v57, v17
	v_cvt_pk_bf16_f32 v108, v4, v5
	v_cvt_pk_bf16_f32 v120, v8, v9
	v_mul_f32_e32 v4, v42, v17
	v_mul_f32_e32 v5, v43, v17
	v_mul_f32_e32 v8, v42, v16
	v_mul_f32_e32 v9, v43, v16
	v_fma_f32 v4, v58, v16, -v4
	v_fma_f32 v5, v59, v16, -v5
	v_fmac_f32_e32 v8, v58, v17
	v_fmac_f32_e32 v9, v59, v17
	v_cvt_pk_bf16_f32 v109, v4, v5
	v_cvt_pk_bf16_f32 v121, v8, v9
	v_mul_f32_e32 v4, v44, v17
	v_mul_f32_e32 v5, v45, v17
	v_mul_f32_e32 v8, v44, v16
	v_mul_f32_e32 v9, v45, v16
	v_fma_f32 v4, v60, v16, -v4
	v_fma_f32 v5, v61, v16, -v5
	v_fmac_f32_e32 v8, v60, v17
	v_fmac_f32_e32 v9, v61, v17
	v_cvt_pk_bf16_f32 v110, v4, v5
	v_cvt_pk_bf16_f32 v122, v8, v9
	v_mul_f32_e32 v4, v46, v17
	v_mul_f32_e32 v5, v47, v17
	v_mul_f32_e32 v8, v46, v16
	v_mul_f32_e32 v9, v47, v16
	v_fma_f32 v4, v62, v16, -v4
	v_fma_f32 v5, v63, v16, -v5
	v_fmac_f32_e32 v8, v62, v17
	v_fmac_f32_e32 v9, v63, v17
	v_cvt_pk_bf16_f32 v111, v4, v5
	v_cvt_pk_bf16_f32 v123, v8, v9
	global_store_dwordx4 v[14:15], v[104:107], off
	global_store_dwordx4 v[14:15], v[108:111], off offset:16
	global_store_dwordx4 v[14:15], v[116:119], off offset:1024
	global_store_dwordx4 v[14:15], v[120:123], off offset:1040
	s_waitcnt vmcnt(4)
	v_xor_b32_e32 v80, 0x80000000, v80
	v_xor_b32_e32 v81, 0x80000000, v81
	v_xor_b32_e32 v82, 0x80000000, v82
	v_xor_b32_e32 v83, 0x80000000, v83
	v_xor_b32_e32 v84, 0x80000000, v84
	v_xor_b32_e32 v85, 0x80000000, v85
	v_xor_b32_e32 v86, 0x80000000, v86
	v_xor_b32_e32 v87, 0x80000000, v87
	v_xor_b32_e32 v88, 0x80000000, v88
	v_xor_b32_e32 v89, 0x80000000, v89
	v_xor_b32_e32 v90, 0x80000000, v90
	v_xor_b32_e32 v91, 0x80000000, v91
	v_xor_b32_e32 v92, 0x80000000, v92
	v_xor_b32_e32 v93, 0x80000000, v93
	v_xor_b32_e32 v94, 0x80000000, v94
	v_xor_b32_e32 v95, 0x80000000, v95
	v_cvt_pk_bf16_f32 v64, v64, v80
	v_cvt_pk_bf16_f32 v65, v65, v81
	v_cvt_pk_bf16_f32 v66, v66, v82
	v_cvt_pk_bf16_f32 v67, v67, v83
	v_cvt_pk_bf16_f32 v68, v68, v84
	v_cvt_pk_bf16_f32 v69, v69, v85
	v_cvt_pk_bf16_f32 v70, v70, v86
	v_cvt_pk_bf16_f32 v71, v71, v87
	v_cvt_pk_bf16_f32 v72, v72, v88
	v_cvt_pk_bf16_f32 v73, v73, v89
	v_cvt_pk_bf16_f32 v74, v74, v90
	v_cvt_pk_bf16_f32 v75, v75, v91
	v_cvt_pk_bf16_f32 v76, v76, v92
	v_cvt_pk_bf16_f32 v77, v77, v93
	v_cvt_pk_bf16_f32 v78, v78, v94
	v_cvt_pk_bf16_f32 v79, v79, v95
	global_store_dword v[100:101], v64, off
	global_store_dword v[100:101], v65, off offset:256
	global_store_dword v[100:101], v66, off offset:512
	global_store_dword v[100:101], v67, off offset:768
	global_store_dword v[100:101], v68, off offset:1024
	global_store_dword v[100:101], v69, off offset:1280
	global_store_dword v[100:101], v70, off offset:1536
	global_store_dword v[100:101], v71, off offset:1792
	global_store_dword v[100:101], v72, off offset:2048
	global_store_dword v[100:101], v73, off offset:2304
	global_store_dword v[100:101], v74, off offset:2560
	global_store_dword v[100:101], v75, off offset:2816
	global_store_dword v[100:101], v76, off offset:3072
	global_store_dword v[100:101], v77, off offset:3328
	global_store_dword v[100:101], v78, off offset:3584
	global_store_dword v[100:101], v79, off offset:3840
	v_mov_b32_e32 v3, 0
